# DP2: phase 0 keeps only layer-0 w_in + layer-0 adaLN tables + rope; w_br/w_out/folds of L0 on idle WGs of L0 sub1, L0 up/down + L1 in/br/out + L1 adaLN on idle WGs of L0 sub4, L1 up/down + L1 folds on
# speedup vs baseline: 1.0970x; 1.0144x over previous
; __device__ void phase_prep(const Params& p, LAS unsigned char* lds) {
;     ...
;     constexpr int I_TR = 2 * T_L, I_POOL = I_TR + 128, I_FOUR = I_POOL + 256, I_MOD = I_FOUR + 192, I_ALL = I_MOD + 1;
;     for (int prep_rep = 0; prep_rep < ((PROBE >= 301 && PROBE <= 304) ? 2 : 1); ++prep_rep)
;     for (int it = blockIdx.x; it < I_ALL; it += gridDim.x) {
;     ...
;         if (prep_rep == 1) { const int cls = (it < I_TR) ? 301 : (it < I_FOUR) ? 302 : (it < I_MOD) ? 303 : 304; if (cls != PROBE) continue; }
;     ...
;         if (it < I_TR) {
.LBB0_14:
	s_andn2_b64 vcc, exec, s[0:1]
	s_cbranch_vccnz .LBB0_735
	v_writelane_b32 v252, s26, 1
	s_movk_i32 s1, 256
	v_writelane_b32 v252, s1, 2
	s_movk_i32 s1, 369
	v_writelane_b32 v252, s1, 3
	s_movk_i32 s1, 0
	v_writelane_b32 v252, s1, 0
	s_movk_i32 s1, 113
	v_writelane_b32 v252, s1, 5
	s_movk_i32 s1, 2063
	v_writelane_b32 v252, s1, 6
	s_movk_i32 s1, 209
	v_writelane_b32 v252, s1, 7
	s_movk_i32 s1, -96
	v_writelane_b32 v252, s1, 8
	s_movk_i32 s1, 368
	v_writelane_b32 v252, s1, 9
	s_movk_i32 s1, 2000
	v_writelane_b32 v252, s1, 10
	s_branch .LBB0_650

; __device__ void phase_prep(const Params& p, LAS unsigned char* lds) {
;     ...
;     constexpr int I_TR = 2 * T_L, I_POOL = I_TR + 128, I_FOUR = I_POOL + 256, I_MOD = I_FOUR + 192, I_ALL = I_MOD + 1;
;     for (int prep_rep = 0; prep_rep < ((PROBE >= 301 && PROBE <= 304) ? 2 : 1); ++prep_rep)
;     for (int it = blockIdx.x; it < I_ALL; it += gridDim.x) {
;     ...
;         if (prep_rep == 1) { const int cls = (it < I_TR) ? 301 : (it < I_FOUR) ? 302 : (it < I_MOD) ? 303 : 304; if (cls != PROBE) continue; }
;     ...
;         if (it < I_TR) {
.Lmy_dp_m0:
	s_cmp_lt_u32 s26, 132
	s_cbranch_scc1 .LBB0_735
	s_sub_i32 s0, s26, 132
	v_writelane_b32 v252, s0, 1
	s_movk_i32 s1, 124
	v_writelane_b32 v252, s1, 2
	s_movk_i32 s1, 288
	v_writelane_b32 v252, s1, 3
	s_movk_i32 s1, 272
	v_writelane_b32 v252, s1, 0
	s_movk_i32 s1, 96
	v_writelane_b32 v252, s1, 5
	s_movk_i32 s1, 1696
	v_writelane_b32 v252, s1, 6
	s_movk_i32 s1, 160
	v_writelane_b32 v252, s1, 7
	s_movk_i32 s1, 1760
	v_writelane_b32 v252, s1, 8
	s_movk_i32 s1, 32767
	v_writelane_b32 v252, s1, 9
	s_movk_i32 s1, 0
	v_writelane_b32 v252, s1, 10
	s_branch .LBB0_650
.Lmy_dp_m1:
	s_cmp_lt_u32 s26, 16
	s_cbranch_scc1 .LBB0_735
	s_sub_i32 s0, s26, 16
	v_writelane_b32 v252, s0, 1
	s_movk_i32 s1, 240
	v_writelane_b32 v252, s1, 2
	s_movk_i32 s1, 992
	v_writelane_b32 v252, s1, 3
	s_movk_i32 s1, 368
	v_writelane_b32 v252, s1, 0
	s_movk_i32 s1, 896
	v_writelane_b32 v252, s1, 5
	s_movk_i32 s1, 1376
	v_writelane_b32 v252, s1, 6
	s_movk_i32 s1, 32767
	v_writelane_b32 v252, s1, 7
	s_movk_i32 s1, 0
	v_writelane_b32 v252, s1, 8
	s_movk_i32 s1, 32767
	v_writelane_b32 v252, s1, 9
	s_movk_i32 s1, 0
	v_writelane_b32 v252, s1, 10
	s_branch .LBB0_650
.Lmy_dp_m2:
	s_cmp_lt_u32 s26, 84
	s_cbranch_scc1 .LBB0_735
	s_sub_i32 s0, s26, 84
	v_writelane_b32 v252, s0, 1
	s_movk_i32 s1, 172
	v_writelane_b32 v252, s1, 2
	s_movk_i32 s1, 720
	v_writelane_b32 v252, s1, 3
	s_movk_i32 s1, 1264
	v_writelane_b32 v252, s1, 0
	s_movk_i32 s1, 528
	v_writelane_b32 v252, s1, 5
	s_movk_i32 s1, 1328
	v_writelane_b32 v252, s1, 6
	s_movk_i32 s1, 592
	v_writelane_b32 v252, s1, 7
	s_movk_i32 s1, 1456
	v_writelane_b32 v252, s1, 8
	s_movk_i32 s1, 32767
	v_writelane_b32 v252, s1, 9
	s_movk_i32 s1, 0
	v_writelane_b32 v252, s1, 10
	s_branch .LBB0_650

; __device__ void phase_prep(const Params& p, LAS unsigned char* lds) {
;     ...
;     for (int it = blockIdx.x; it < I_ALL; it += gridDim.x) {
;     ...
;         if (prep_rep == 1) { const int cls = (it < I_TR) ? 301 : (it < I_FOUR) ? 302 : (it < I_MOD) ? 303 : 304; if (cls != PROBE) continue; }
;     ...
;         if (it < I_TR) {
;             const int l = it / T_L; int j = it % T_L;
;             unsigned char* wb = p.ws + OFF_W + (size_t)l * LW;
.Lmy_dp_first:
	v_readlane_b32 s88, v252, 1
	v_readlane_b32 s89, v252, 3
	s_nop 3
	s_cmp_ge_i32 s88, s89
	s_cbranch_scc1 .LBB0_734
	v_readlane_b32 s17, v252, 0
	v_readlane_b32 s89, v252, 5
	s_nop 3
	s_cmp_lt_i32 s88, s89
	s_cbranch_scc1 .Lmy_dp_it
	v_readlane_b32 s17, v252, 6
	v_readlane_b32 s89, v252, 7
	s_nop 3
	s_cmp_lt_i32 s88, s89
	s_cbranch_scc1 .Lmy_dp_it
	v_readlane_b32 s17, v252, 8
	v_readlane_b32 s89, v252, 9
	s_nop 3
	s_cmp_lt_i32 s88, s89
	s_cbranch_scc1 .Lmy_dp_it
	v_readlane_b32 s17, v252, 10
	s_nop 3
.Lmy_dp_it:
	s_add_i32 s17, s17, s88
	v_readlane_b32 s8, v252, 4
	s_nop 3
	s_add_i32 s8, s8, s17
